# layer-1 cache conversion (f32->bf16) moved off the serial path: hand-written streaming loop run at the end of layer 0's out phase by the 384 workgroups without a third tile; the separate per-element l
# speedup vs baseline: 1.0072x; 1.0072x over previous
; DI int otid() { int t = __builtin_amdgcn_workitem_id_x(); asm volatile("" : "+v"(t)); return t; }
; DI void convert_caches(const Params& p, int l) {
;   const int tid = otid();
;   const long total = (long)32 * 2048 * 40;
;   for (long e = (long)blockIdx.x * 256 + tid; e < total; e += (long)gridDim.x * 256) {
;     const int row = (int)(e / 40), c = (int)(e - (long)row * 40);
;     const int b = row >> 11, pos = row & 2047;
;     const size_t drow = (size_t)16384 + (size_t)b * 2112 + pos;
;     const size_t srow = (size_t)(l * 32 + b) * 2048 + pos;
;     if (c < 16) *(bf16x8*)(p.KB + drow * 128 + c * 8) = cvt8(p.cache_k + srow * 128 + c * 8);
;     else if (c < 32) *(bf16x8*)(p.VB + drow * 128 + (c - 16) * 8) = cvt8(p.cache_v + srow * 128 + (c - 16) * 8);
;     else *(bf16x8*)(p.KIB + drow * 64 + (c - 32) * 8) = cvt8(p.cache_kidx + srow * 64 + (c - 32) * 8);
;   }
; }
; __global__ void __launch_bounds__(256, 2) mega(Params pk) {
;     ...
;     if (l == 1) { norm_phase(p, 1); convert_caches(p, 1); gbar(gb); }
.LBB0_137:
	s_or_b64 exec, exec, s[4:5]
	s_branch .LBB0_148

; DI int otid() { int t = __builtin_amdgcn_workitem_id_x(); asm volatile("" : "+v"(t)); return t; }
; DI void convert_caches(const Params& p, int l) {
;   const int tid = otid();
;   const long total = (long)32 * 2048 * 40;
;   for (long e = (long)blockIdx.x * 256 + tid; e < total; e += (long)gridDim.x * 256) {
;     const int row = (int)(e / 40), c = (int)(e - (long)row * 40);
;     const int b = row >> 11, pos = row & 2047;
;     const size_t drow = (size_t)16384 + (size_t)b * 2112 + pos;
;     const size_t srow = (size_t)(l * 32 + b) * 2048 + pos;
;     if (c < 16) *(bf16x8*)(p.KB + drow * 128 + c * 8) = cvt8(p.cache_k + srow * 128 + c * 8);
;     else if (c < 32) *(bf16x8*)(p.VB + drow * 128 + (c - 16) * 8) = cvt8(p.cache_v + srow * 128 + (c - 16) * 8);
;     else *(bf16x8*)(p.KIB + drow * 64 + (c - 32) * 8) = cvt8(p.cache_kidx + srow * 64 + (c - 32) * 8);
;   }
; }
.LBB0_1867:
	v_readlane_b32 s4, v254, 51
	v_readlane_b32 s98, v254, 0
	s_nop 1
	s_cmp_lg_u32 s4, 0
	s_cbranch_scc1 .Lcv_skip
	s_cmp_lt_u32 s98, 128
	s_cbranch_scc1 .Lcv_skip
	s_load_dwordx2 s[4:5], s[0:1], 0x18
	s_load_dwordx2 s[6:7], s[0:1], 0x20
	s_load_dwordx2 s[8:9], s[0:1], 0x28
	s_load_dwordx2 s[10:11], s[0:1], 0x168
	s_load_dwordx2 s[12:13], s[0:1], 0x170
	s_load_dwordx2 s[14:15], s[0:1], 0x178
	v_lshrrev_b32_e32 v4, 6, v182
	v_and_b32_e32 v5, 63, v182
	s_nop 0
	v_readfirstlane_b32 s99, v4
	v_lshrrev_b32_e32 v40, 4, v5
	v_and_b32_e32 v41, 15, v5
	s_sub_u32 s98, s98, 128
	s_lshl_b32 s98, s98, 2
	s_add_u32 s98, s98, s99
	s_waitcnt lgkmcnt(0)
	s_add_u32 s4, s4, 0x2000000
	s_addc_u32 s5, s5, 0
	s_add_u32 s6, s6, 0x2000000
	s_addc_u32 s7, s7, 0
	s_add_u32 s8, s8, 0x1000000
	s_addc_u32 s9, s9, 0
.Lcv_loop:
	s_lshl_b32 s101, s98, 2
	v_add_u32_e32 v42, s101, v40
	v_lshlrev_b32_e32 v43, 9, v42
	v_lshl_add_u32 v43, v41, 5, v43
	v_lshlrev_b32_e32 v44, 8, v42
	v_lshl_add_u32 v44, v41, 4, v44
	v_lshrrev_b32_e32 v45, 11, v42
	v_lshl_add_u32 v45, v45, 6, v42
	v_add_u32_e32 v45, 0x4000, v45
	v_lshlrev_b32_e32 v46, 8, v45
	v_lshl_add_u32 v46, v41, 4, v46
	v_lshlrev_b32_e32 v47, 7, v45
	v_lshl_add_u32 v47, v41, 3, v47
	global_load_dwordx4 v[48:51], v43, s[4:5]
	global_load_dwordx4 v[52:55], v43, s[4:5] offset:16
	global_load_dwordx4 v[56:59], v43, s[6:7]
	global_load_dwordx4 v[60:63], v43, s[6:7] offset:16
	global_load_dwordx4 v[64:67], v44, s[8:9]
	s_add_u32 s100, s98, 0x600
	s_cmp_lt_u32 s100, 0x4000
	s_cbranch_scc0 .Lcv_one
	s_lshl_b32 s101, s100, 2
	v_add_u32_e32 v68, s101, v40
	v_lshlrev_b32_e32 v69, 9, v68
	v_lshl_add_u32 v69, v41, 5, v69
	v_lshlrev_b32_e32 v70, 8, v68
	v_lshl_add_u32 v70, v41, 4, v70
	v_lshrrev_b32_e32 v71, 11, v68
	v_lshl_add_u32 v71, v71, 6, v68
	v_add_u32_e32 v71, 0x4000, v71
	v_lshlrev_b32_e32 v72, 8, v71
	v_lshl_add_u32 v72, v41, 4, v72
	v_lshlrev_b32_e32 v73, 7, v71
	v_lshl_add_u32 v73, v41, 3, v73
	global_load_dwordx4 v[74:77], v69, s[4:5]
	global_load_dwordx4 v[78:81], v69, s[4:5] offset:16
	global_load_dwordx4 v[82:85], v69, s[6:7]
	global_load_dwordx4 v[86:89], v69, s[6:7] offset:16
	global_load_dwordx4 v[90:93], v70, s[8:9]
	s_waitcnt vmcnt(5)
	v_cvt_pk_bf16_f32 v48, v48, v49
	v_cvt_pk_bf16_f32 v49, v50, v51
	v_cvt_pk_bf16_f32 v50, v52, v53
	v_cvt_pk_bf16_f32 v51, v54, v55
	v_cvt_pk_bf16_f32 v56, v56, v57
	v_cvt_pk_bf16_f32 v57, v58, v59
	v_cvt_pk_bf16_f32 v58, v60, v61
	v_cvt_pk_bf16_f32 v59, v62, v63
	v_cvt_pk_bf16_f32 v64, v64, v65
	v_cvt_pk_bf16_f32 v65, v66, v67
	global_store_dwordx4 v46, v[48:51], s[10:11]
	global_store_dwordx4 v46, v[56:59], s[12:13]
	global_store_dwordx2 v47, v[64:65], s[14:15]
	s_waitcnt vmcnt(3)
	v_cvt_pk_bf16_f32 v74, v74, v75
	v_cvt_pk_bf16_f32 v75, v76, v77
	v_cvt_pk_bf16_f32 v76, v78, v79
	v_cvt_pk_bf16_f32 v77, v80, v81
	v_cvt_pk_bf16_f32 v82, v82, v83
	v_cvt_pk_bf16_f32 v83, v84, v85
	v_cvt_pk_bf16_f32 v84, v86, v87
	v_cvt_pk_bf16_f32 v85, v88, v89
	v_cvt_pk_bf16_f32 v90, v90, v91
	v_cvt_pk_bf16_f32 v91, v92, v93
	global_store_dwordx4 v72, v[74:77], s[10:11]
	global_store_dwordx4 v72, v[82:85], s[12:13]
	global_store_dwordx2 v73, v[90:91], s[14:15]
	s_add_u32 s98, s98, 0xc00
	s_cmp_lt_u32 s98, 0x4000
	s_cbranch_scc1 .Lcv_loop
	s_branch .Lcv_skip
.Lcv_one:
	s_waitcnt vmcnt(0)
	v_cvt_pk_bf16_f32 v48, v48, v49
	v_cvt_pk_bf16_f32 v49, v50, v51
	v_cvt_pk_bf16_f32 v50, v52, v53
	v_cvt_pk_bf16_f32 v51, v54, v55
	v_cvt_pk_bf16_f32 v56, v56, v57
	v_cvt_pk_bf16_f32 v57, v58, v59
	v_cvt_pk_bf16_f32 v58, v60, v61
	v_cvt_pk_bf16_f32 v59, v62, v63
	v_cvt_pk_bf16_f32 v64, v64, v65
	v_cvt_pk_bf16_f32 v65, v66, v67
	global_store_dwordx4 v46, v[48:51], s[10:11]
	global_store_dwordx4 v46, v[56:59], s[12:13]
	global_store_dwordx2 v47, v[64:65], s[14:15]
